# speedup vs baseline: 1.1313x; 1.0039x over previous
; __device__ __forceinline__ void phase_select(const Params& p, int layer, char* smraw) {
;     ...
;   {
;     const u16* src = p.Sub + (size_t)layer * 2 * 128 * 128;
;     __syncthreads();
;     for (int c = tid; c < 4096; c += NTHREADS) {
;       const int row = c >> 4, ch = c & 15;
;       *(u32x4*)(Subs + row * 136 + ch * 8) = *(const u32x4*)(src + row * 128 + ch * 8);
;     }
;     __syncthreads();
;   }
.LBB0_625:
	s_or_b64 exec, exec, s[0:1]
	v_mov_b32_e32 v2, v189
	s_movk_i32 s0, 0x1000
	s_barrier
	s_nop 0
	v_cmp_gt_i32_e32 vcc, s0, v2
	s_barrier
	s_and_saveexec_b64 s[0:1], vcc
	s_cbranch_execz .LBB0_628
	v_lshrrev_b32_e32 v5, 4, v2
	v_and_b32_e32 v0, 15, v2
	v_lshlrev_b32_e32 v0, 4, v0
	v_lshl_add_u32 v3, v5, 8, v0
	v_mul_u32_u24_e32 v4, 0x110, v5
	v_add_u32_e32 v4, v4, v0
	global_load_dwordx4 v[16:19], v3, s[86:87]
	v_add_u32_e32 v7, 0x1000, v3
	global_load_dwordx4 v[20:23], v7, s[86:87]
	v_add_u32_e32 v6, 0x2000, v3
	global_load_dwordx4 v[24:27], v6, s[86:87]
	v_add_u32_e32 v7, 0x3000, v3
	global_load_dwordx4 v[28:31], v7, s[86:87]
	v_add_u32_e32 v6, 0x4000, v3
	global_load_dwordx4 v[32:35], v6, s[86:87]
	v_add_u32_e32 v7, 0x5000, v3
	global_load_dwordx4 v[36:39], v7, s[86:87]
	v_add_u32_e32 v6, 0x6000, v3
	global_load_dwordx4 v[40:43], v6, s[86:87]
	v_add_u32_e32 v7, 0x7000, v3
	global_load_dwordx4 v[44:47], v7, s[86:87]
	v_add_u32_e32 v6, 0x8000, v3
	global_load_dwordx4 v[48:51], v6, s[86:87]
	v_add_u32_e32 v7, 0x9000, v3
	global_load_dwordx4 v[52:55], v7, s[86:87]
	v_add_u32_e32 v6, 0xa000, v3
	global_load_dwordx4 v[56:59], v6, s[86:87]
	v_add_u32_e32 v7, 0xb000, v3
	global_load_dwordx4 v[60:63], v7, s[86:87]
	v_add_u32_e32 v6, 0xc000, v3
	global_load_dwordx4 v[64:67], v6, s[86:87]
	v_add_u32_e32 v7, 0xd000, v3
	global_load_dwordx4 v[68:71], v7, s[86:87]
	v_add_u32_e32 v6, 0xe000, v3
	global_load_dwordx4 v[72:75], v6, s[86:87]
	v_add_u32_e32 v7, 0xf000, v3
	global_load_dwordx4 v[76:79], v7, s[86:87]
	s_waitcnt vmcnt(0)
	ds_write_b128 v4, v[16:19]
	ds_write_b128 v4, v[20:23] offset:4352
	ds_write_b128 v4, v[24:27] offset:8704
	ds_write_b128 v4, v[28:31] offset:13056
	ds_write_b128 v4, v[32:35] offset:17408
	ds_write_b128 v4, v[36:39] offset:21760
	ds_write_b128 v4, v[40:43] offset:26112
	ds_write_b128 v4, v[44:47] offset:30464
	ds_write_b128 v4, v[48:51] offset:34816
	ds_write_b128 v4, v[52:55] offset:39168
	ds_write_b128 v4, v[56:59] offset:43520
	ds_write_b128 v4, v[60:63] offset:47872
	ds_write_b128 v4, v[64:67] offset:52224
	ds_write_b128 v4, v[68:71] offset:56576
	ds_write_b128 v4, v[72:75] offset:60928
	ds_write_b128 v4, v[76:79] offset:65280

; __device__ __forceinline__ void phase_select(const Params& p, int layer, char* smraw) {
;     ...
;   {
;     const u16* src = p.Sub + (size_t)layer * 2 * 128 * 128;
;     __syncthreads();
;     for (int c = tid; c < 4096; c += NTHREADS) {
;       const int row = c >> 4, ch = c & 15;
;       *(u32x4*)(Subs + row * 136 + ch * 8) = *(const u32x4*)(src + row * 128 + ch * 8);
;     }
;     __syncthreads();
;   }
.LBB0_1220:
	s_or_b64 exec, exec, s[0:1]
	v_mov_b32_e32 v2, v189
	s_movk_i32 s0, 0x1000
	s_barrier
	s_nop 0
	v_cmp_gt_i32_e32 vcc, s0, v2
	s_barrier
	s_and_saveexec_b64 s[0:1], vcc
	s_cbranch_execz .LBB0_1223
	s_add_u32 s6, s86, 0x10000
	s_addc_u32 s7, s87, 0
	v_lshrrev_b32_e32 v5, 4, v2
	v_and_b32_e32 v0, 15, v2
	v_lshlrev_b32_e32 v0, 4, v0
	v_lshl_add_u32 v3, v5, 8, v0
	v_mul_u32_u24_e32 v4, 0x110, v5
	v_add_u32_e32 v4, v4, v0
	global_load_dwordx4 v[16:19], v3, s[6:7]
	v_add_u32_e32 v7, 0x1000, v3
	global_load_dwordx4 v[20:23], v7, s[6:7]
	v_add_u32_e32 v6, 0x2000, v3
	global_load_dwordx4 v[24:27], v6, s[6:7]
	v_add_u32_e32 v7, 0x3000, v3
	global_load_dwordx4 v[28:31], v7, s[6:7]
	v_add_u32_e32 v6, 0x4000, v3
	global_load_dwordx4 v[32:35], v6, s[6:7]
	v_add_u32_e32 v7, 0x5000, v3
	global_load_dwordx4 v[36:39], v7, s[6:7]
	v_add_u32_e32 v6, 0x6000, v3
	global_load_dwordx4 v[40:43], v6, s[6:7]
	v_add_u32_e32 v7, 0x7000, v3
	global_load_dwordx4 v[44:47], v7, s[6:7]
	v_add_u32_e32 v6, 0x8000, v3
	global_load_dwordx4 v[48:51], v6, s[6:7]
	v_add_u32_e32 v7, 0x9000, v3
	global_load_dwordx4 v[52:55], v7, s[6:7]
	v_add_u32_e32 v6, 0xa000, v3
	global_load_dwordx4 v[56:59], v6, s[6:7]
	v_add_u32_e32 v7, 0xb000, v3
	global_load_dwordx4 v[60:63], v7, s[6:7]
	v_add_u32_e32 v6, 0xc000, v3
	global_load_dwordx4 v[64:67], v6, s[6:7]
	v_add_u32_e32 v7, 0xd000, v3
	global_load_dwordx4 v[68:71], v7, s[6:7]
	v_add_u32_e32 v6, 0xe000, v3
	global_load_dwordx4 v[72:75], v6, s[6:7]
	v_add_u32_e32 v7, 0xf000, v3
	global_load_dwordx4 v[76:79], v7, s[6:7]
	s_waitcnt vmcnt(0)
	ds_write_b128 v4, v[16:19]
	ds_write_b128 v4, v[20:23] offset:4352
	ds_write_b128 v4, v[24:27] offset:8704
	ds_write_b128 v4, v[28:31] offset:13056
	ds_write_b128 v4, v[32:35] offset:17408
	ds_write_b128 v4, v[36:39] offset:21760
	ds_write_b128 v4, v[40:43] offset:26112
	ds_write_b128 v4, v[44:47] offset:30464
	ds_write_b128 v4, v[48:51] offset:34816
	ds_write_b128 v4, v[52:55] offset:39168
	ds_write_b128 v4, v[56:59] offset:43520
	ds_write_b128 v4, v[60:63] offset:47872
	ds_write_b128 v4, v[64:67] offset:52224
	ds_write_b128 v4, v[68:71] offset:56576
	ds_write_b128 v4, v[72:75] offset:60928
	ds_write_b128 v4, v[76:79] offset:65280
